# DPP/permlane instead of LDS round trips: the xor-16/xor-32 ds_bpermute shuffles of the GU epilogue row-norm reduction replaced by v_mov + v_permlane16/32_swap
# speedup vs baseline: 1.0157x; 1.0157x over previous
.LBB0_1436:
	s_add_u32 s28, s6, 0xfffc0080
	s_addc_u32 s29, s7, -1
	s_add_i32 s71, 0, 0x10000
	ds_read_b128 v[128:131], v174
	ds_read_b128 v[132:135], v174 offset:1024
	ds_read_b128 v[136:139], v174 offset:2048
	ds_read_b128 v[140:143], v174 offset:3072
	s_cmp_eq_u32 s70, 12
	s_cselect_b32 s53, s17, s29
	s_cselect_b32 s52, s66, s28
	s_cselect_b32 s51, s13, s69
	s_cselect_b32 s50, s67, s68
	s_add_i32 m0, s56, 0xc000
	ds_read_b128 v[144:147], v201
	ds_read_b128 v[152:155], v201 offset:2048
	ds_read_b128 v[170:173], v201 offset:4096
	ds_read_b128 v[192:195], v201 offset:6144
	ds_read_b128 v[148:151], v201 offset:1024
	ds_read_b128 v[166:169], v201 offset:3072
	ds_read_b128 v[188:191], v201 offset:5120
	ds_read_b128 v[202:205], v201 offset:7168
	global_load_lds_dwordx4 v162, s[6:7]
	s_add_i32 m0, s56, 0xe000
	s_nop 0
	global_load_lds_dwordx4 v164, s[6:7]
	s_waitcnt lgkmcnt(8)
	s_barrier
	s_waitcnt lgkmcnt(7)
	v_mfma_f32_16x16x32_bf16 v[124:127], v[128:131], v[144:147], v[124:127]
	v_mfma_f32_16x16x32_bf16 v[116:119], v[136:139], v[144:147], v[116:119]
	s_waitcnt lgkmcnt(6)
	v_mfma_f32_16x16x32_bf16 v[108:111], v[128:131], v[152:155], v[108:111]
	v_mfma_f32_16x16x32_bf16 v[100:103], v[136:139], v[152:155], v[100:103]
	s_waitcnt lgkmcnt(5)
	v_mfma_f32_16x16x32_bf16 v[92:95], v[128:131], v[170:173], v[92:95]
	v_mfma_f32_16x16x32_bf16 v[84:87], v[136:139], v[170:173], v[84:87]
	s_waitcnt lgkmcnt(4)
	v_mfma_f32_16x16x32_bf16 v[76:79], v[128:131], v[192:195], v[76:79]
	v_mfma_f32_16x16x32_bf16 v[68:71], v[136:139], v[192:195], v[68:71]
	s_waitcnt lgkmcnt(3)
	v_mfma_f32_16x16x32_bf16 v[124:127], v[132:135], v[148:151], v[124:127]
	v_mfma_f32_16x16x32_bf16 v[116:119], v[140:143], v[148:151], v[116:119]
	s_waitcnt lgkmcnt(2)
	v_mfma_f32_16x16x32_bf16 v[108:111], v[132:135], v[166:169], v[108:111]
	v_mfma_f32_16x16x32_bf16 v[100:103], v[140:143], v[166:169], v[100:103]
	s_waitcnt lgkmcnt(1)
	v_mfma_f32_16x16x32_bf16 v[92:95], v[132:135], v[188:191], v[92:95]
	v_mfma_f32_16x16x32_bf16 v[84:87], v[140:143], v[188:191], v[84:87]
	s_waitcnt lgkmcnt(0)
	v_mfma_f32_16x16x32_bf16 v[76:79], v[132:135], v[202:205], v[76:79]
	v_mfma_f32_16x16x32_bf16 v[68:71], v[140:143], v[202:205], v[68:71]
	s_barrier
	s_add_i32 s28, 0, 0x14000
	s_add_i32 s29, s71, s55
	ds_read_b128 v[206:209], v174 offset:16384
	ds_read_b128 v[210:213], v174 offset:17408
	ds_read_b128 v[214:217], v174 offset:18432
	ds_read_b128 v[232:235], v174 offset:19456
	s_mov_b32 m0, s29
	s_nop 0
	global_load_lds_dwordx4 v176, s[50:51]
	s_add_i32 m0, s29, 0x2000
	s_nop 0
	global_load_lds_dwordx4 v160, s[50:51]
	s_barrier
	s_waitcnt lgkmcnt(3)
	v_mfma_f32_16x16x32_bf16 v[120:123], v[206:209], v[144:147], v[120:123]
	s_waitcnt lgkmcnt(1)
	v_mfma_f32_16x16x32_bf16 v[112:115], v[214:217], v[144:147], v[112:115]
	v_mfma_f32_16x16x32_bf16 v[104:107], v[206:209], v[152:155], v[104:107]
	v_mfma_f32_16x16x32_bf16 v[96:99], v[214:217], v[152:155], v[96:99]
	v_mfma_f32_16x16x32_bf16 v[88:91], v[206:209], v[170:173], v[88:91]
	v_mfma_f32_16x16x32_bf16 v[80:83], v[214:217], v[170:173], v[80:83]
	v_mfma_f32_16x16x32_bf16 v[72:75], v[206:209], v[192:195], v[72:75]
	v_mfma_f32_16x16x32_bf16 v[64:67], v[214:217], v[192:195], v[64:67]
	v_mfma_f32_16x16x32_bf16 v[120:123], v[210:213], v[148:151], v[120:123]
	s_waitcnt lgkmcnt(0)
	v_mfma_f32_16x16x32_bf16 v[112:115], v[232:235], v[148:151], v[112:115]
	v_mfma_f32_16x16x32_bf16 v[104:107], v[210:213], v[166:169], v[104:107]
	v_mfma_f32_16x16x32_bf16 v[96:99], v[232:235], v[166:169], v[96:99]
	v_mfma_f32_16x16x32_bf16 v[88:91], v[210:213], v[188:191], v[88:91]
	v_mfma_f32_16x16x32_bf16 v[80:83], v[232:235], v[188:191], v[80:83]
	v_mfma_f32_16x16x32_bf16 v[72:75], v[210:213], v[202:205], v[72:75]
	v_mfma_f32_16x16x32_bf16 v[64:67], v[232:235], v[202:205], v[64:67]
	s_mov_b32 m0, s56
	s_barrier
	ds_read_b128 v[144:147], v201 offset:16384
	ds_read_b128 v[152:155], v201 offset:18432
	ds_read_b128 v[170:173], v201 offset:20480
	ds_read_b128 v[192:195], v201 offset:22528
	ds_read_b128 v[148:151], v201 offset:17408
	ds_read_b128 v[166:169], v201 offset:19456
	ds_read_b128 v[188:191], v201 offset:21504
	ds_read_b128 v[202:205], v201 offset:23552
	global_load_lds_dwordx4 v156, s[52:53]
	s_mov_b32 m0, s57
	s_nop 0
	global_load_lds_dwordx4 v158, s[52:53]
	s_barrier
	s_waitcnt lgkmcnt(7)
	v_mfma_f32_16x16x32_bf16 v[60:63], v[128:131], v[144:147], v[60:63]
	v_mfma_f32_16x16x32_bf16 v[52:55], v[136:139], v[144:147], v[52:55]
	s_waitcnt lgkmcnt(6)
	v_mfma_f32_16x16x32_bf16 v[44:47], v[128:131], v[152:155], v[44:47]
	v_mfma_f32_16x16x32_bf16 v[36:39], v[136:139], v[152:155], v[36:39]
	s_waitcnt lgkmcnt(5)
	v_mfma_f32_16x16x32_bf16 v[28:31], v[128:131], v[170:173], v[28:31]
	v_mfma_f32_16x16x32_bf16 v[20:23], v[136:139], v[170:173], v[20:23]
	s_waitcnt lgkmcnt(4)
	v_mfma_f32_16x16x32_bf16 v[12:15], v[128:131], v[192:195], v[12:15]
	v_mfma_f32_16x16x32_bf16 v[4:7], v[136:139], v[192:195], v[4:7]
	s_waitcnt lgkmcnt(3)
	v_mfma_f32_16x16x32_bf16 v[60:63], v[132:135], v[148:151], v[60:63]
	v_mfma_f32_16x16x32_bf16 v[52:55], v[140:143], v[148:151], v[52:55]
	s_waitcnt lgkmcnt(2)
	v_mfma_f32_16x16x32_bf16 v[44:47], v[132:135], v[166:169], v[44:47]
	v_mfma_f32_16x16x32_bf16 v[36:39], v[140:143], v[166:169], v[36:39]
	s_waitcnt lgkmcnt(1)
	v_mfma_f32_16x16x32_bf16 v[28:31], v[132:135], v[188:191], v[28:31]
	v_mfma_f32_16x16x32_bf16 v[20:23], v[140:143], v[188:191], v[20:23]
	s_waitcnt lgkmcnt(0)
	v_mfma_f32_16x16x32_bf16 v[12:15], v[132:135], v[202:205], v[12:15]
	v_mfma_f32_16x16x32_bf16 v[4:7], v[140:143], v[202:205], v[4:7]
	s_barrier
	s_add_u32 s72, s50, 0x40000
	s_addc_u32 s73, s51, 0
	s_add_i32 s28, s28, s55
	s_mov_b32 m0, s28
	s_nop 0
	global_load_lds_dwordx4 v176, s[72:73]
	s_add_i32 m0, s28, 0x2000
	s_nop 0
	global_load_lds_dwordx4 v160, s[72:73]
	s_waitcnt vmcnt(6)
	s_barrier
	v_mfma_f32_16x16x32_bf16 v[56:59], v[206:209], v[144:147], v[56:59]
	v_mfma_f32_16x16x32_bf16 v[48:51], v[214:217], v[144:147], v[48:51]
	v_mfma_f32_16x16x32_bf16 v[40:43], v[206:209], v[152:155], v[40:43]
	v_mfma_f32_16x16x32_bf16 v[32:35], v[214:217], v[152:155], v[32:35]
	v_mfma_f32_16x16x32_bf16 v[24:27], v[206:209], v[170:173], v[24:27]
	v_mfma_f32_16x16x32_bf16 v[16:19], v[214:217], v[170:173], v[16:19]
	v_mfma_f32_16x16x32_bf16 v[8:11], v[206:209], v[192:195], v[8:11]
	v_mfma_f32_16x16x32_bf16 v[0:3], v[214:217], v[192:195], v[0:3]
	v_mfma_f32_16x16x32_bf16 v[56:59], v[210:213], v[148:151], v[56:59]
	v_mfma_f32_16x16x32_bf16 v[48:51], v[232:235], v[148:151], v[48:51]
	v_mfma_f32_16x16x32_bf16 v[40:43], v[210:213], v[166:169], v[40:43]
	v_mfma_f32_16x16x32_bf16 v[32:35], v[232:235], v[166:169], v[32:35]
	v_mfma_f32_16x16x32_bf16 v[24:27], v[210:213], v[188:191], v[24:27]
	v_mfma_f32_16x16x32_bf16 v[16:19], v[232:235], v[188:191], v[16:19]
	v_mfma_f32_16x16x32_bf16 v[8:11], v[210:213], v[202:205], v[8:11]
	v_mfma_f32_16x16x32_bf16 v[0:3], v[232:235], v[202:205], v[0:3]
	s_add_i32 s28, 0, 0x18000
	s_barrier
	ds_read_b128 v[128:131], v174 offset:32768
	ds_read_b128 v[132:135], v174 offset:33792
	ds_read_b128 v[136:139], v174 offset:34816
	ds_read_b128 v[140:143], v174 offset:35840
	s_add_u32 s98, s52, 0x40000
	s_addc_u32 s99, s53, 0
	s_mov_b32 m0, s58
	ds_read_b128 v[144:147], v201 offset:32768
	ds_read_b128 v[152:155], v201 offset:34816
	ds_read_b128 v[170:173], v201 offset:36864
	ds_read_b128 v[192:195], v201 offset:38912
	ds_read_b128 v[148:151], v201 offset:33792
	ds_read_b128 v[166:169], v201 offset:35840
	ds_read_b128 v[188:191], v201 offset:37888
	ds_read_b128 v[202:205], v201 offset:39936
	global_load_lds_dwordx4 v156, s[98:99]
	s_mov_b32 m0, s59
	s_nop 0
	global_load_lds_dwordx4 v158, s[98:99]
	s_waitcnt lgkmcnt(8)
	s_barrier
	s_waitcnt lgkmcnt(7)
	v_mfma_f32_16x16x32_bf16 v[124:127], v[128:131], v[144:147], v[124:127]
	v_mfma_f32_16x16x32_bf16 v[116:119], v[136:139], v[144:147], v[116:119]
	s_waitcnt lgkmcnt(6)
	v_mfma_f32_16x16x32_bf16 v[108:111], v[128:131], v[152:155], v[108:111]
	v_mfma_f32_16x16x32_bf16 v[100:103], v[136:139], v[152:155], v[100:103]
	s_waitcnt lgkmcnt(5)
	v_mfma_f32_16x16x32_bf16 v[92:95], v[128:131], v[170:173], v[92:95]
	v_mfma_f32_16x16x32_bf16 v[84:87], v[136:139], v[170:173], v[84:87]
	s_waitcnt lgkmcnt(4)
	v_mfma_f32_16x16x32_bf16 v[76:79], v[128:131], v[192:195], v[76:79]
	v_mfma_f32_16x16x32_bf16 v[68:71], v[136:139], v[192:195], v[68:71]
	s_waitcnt lgkmcnt(3)
	v_mfma_f32_16x16x32_bf16 v[124:127], v[132:135], v[148:151], v[124:127]
	v_mfma_f32_16x16x32_bf16 v[116:119], v[140:143], v[148:151], v[116:119]
	s_waitcnt lgkmcnt(2)
	v_mfma_f32_16x16x32_bf16 v[108:111], v[132:135], v[166:169], v[108:111]
	v_mfma_f32_16x16x32_bf16 v[100:103], v[140:143], v[166:169], v[100:103]
	s_waitcnt lgkmcnt(1)
	v_mfma_f32_16x16x32_bf16 v[92:95], v[132:135], v[188:191], v[92:95]
	v_mfma_f32_16x16x32_bf16 v[84:87], v[140:143], v[188:191], v[84:87]
	s_waitcnt lgkmcnt(0)
	v_mfma_f32_16x16x32_bf16 v[76:79], v[132:135], v[202:205], v[76:79]
	v_mfma_f32_16x16x32_bf16 v[68:71], v[140:143], v[202:205], v[68:71]
	s_barrier
	s_add_i32 s29, 0, 0x1c000
	s_add_i32 s28, s28, s55
	s_add_i32 m0, s28, 0xffffff80
	ds_read_b128 v[206:209], v174 offset:49152
	ds_read_b128 v[210:213], v174 offset:50176
	ds_read_b128 v[214:217], v174 offset:51200
	ds_read_b128 v[232:235], v174 offset:52224
	global_load_lds_dwordx4 v176, s[50:51] offset:128
	s_add_i32 m0, s28, 0x1f80
	s_nop 0
	global_load_lds_dwordx4 v160, s[50:51] offset:128
	s_barrier
	s_waitcnt lgkmcnt(3)
	v_mfma_f32_16x16x32_bf16 v[120:123], v[206:209], v[144:147], v[120:123]
	s_waitcnt lgkmcnt(1)
	v_mfma_f32_16x16x32_bf16 v[112:115], v[214:217], v[144:147], v[112:115]
	v_mfma_f32_16x16x32_bf16 v[104:107], v[206:209], v[152:155], v[104:107]
	v_mfma_f32_16x16x32_bf16 v[96:99], v[214:217], v[152:155], v[96:99]
	v_mfma_f32_16x16x32_bf16 v[88:91], v[206:209], v[170:173], v[88:91]
	v_mfma_f32_16x16x32_bf16 v[80:83], v[214:217], v[170:173], v[80:83]
	v_mfma_f32_16x16x32_bf16 v[72:75], v[206:209], v[192:195], v[72:75]
	v_mfma_f32_16x16x32_bf16 v[64:67], v[214:217], v[192:195], v[64:67]
	v_mfma_f32_16x16x32_bf16 v[120:123], v[210:213], v[148:151], v[120:123]
	s_waitcnt lgkmcnt(0)
	v_mfma_f32_16x16x32_bf16 v[112:115], v[232:235], v[148:151], v[112:115]
	v_mfma_f32_16x16x32_bf16 v[104:107], v[210:213], v[166:169], v[104:107]
	v_mfma_f32_16x16x32_bf16 v[96:99], v[232:235], v[166:169], v[96:99]
	v_mfma_f32_16x16x32_bf16 v[88:91], v[210:213], v[188:191], v[88:91]
	v_mfma_f32_16x16x32_bf16 v[80:83], v[232:235], v[188:191], v[80:83]
	v_mfma_f32_16x16x32_bf16 v[72:75], v[210:213], v[202:205], v[72:75]
	v_mfma_f32_16x16x32_bf16 v[64:67], v[232:235], v[202:205], v[64:67]
	s_add_i32 m0, s62, 0xffffff80
	s_barrier
	ds_read_b128 v[144:147], v201 offset:49152
	ds_read_b128 v[152:155], v201 offset:51200
	ds_read_b128 v[170:173], v201 offset:53248
	ds_read_b128 v[192:195], v201 offset:55296
	ds_read_b128 v[148:151], v201 offset:50176
	ds_read_b128 v[166:169], v201 offset:52224
	ds_read_b128 v[188:191], v201 offset:54272
	ds_read_b128 v[202:205], v201 offset:56320
	global_load_lds_dwordx4 v156, s[52:53] offset:128
	s_add_i32 m0, s63, 0xffffff80
	s_nop 0
	global_load_lds_dwordx4 v158, s[52:53] offset:128
	s_barrier
	s_waitcnt lgkmcnt(7)
	v_mfma_f32_16x16x32_bf16 v[60:63], v[128:131], v[144:147], v[60:63]
	v_mfma_f32_16x16x32_bf16 v[52:55], v[136:139], v[144:147], v[52:55]
	s_waitcnt lgkmcnt(6)
	v_mfma_f32_16x16x32_bf16 v[44:47], v[128:131], v[152:155], v[44:47]
	v_mfma_f32_16x16x32_bf16 v[36:39], v[136:139], v[152:155], v[36:39]
	s_waitcnt lgkmcnt(5)
	v_mfma_f32_16x16x32_bf16 v[28:31], v[128:131], v[170:173], v[28:31]
	v_mfma_f32_16x16x32_bf16 v[20:23], v[136:139], v[170:173], v[20:23]
	s_waitcnt lgkmcnt(4)
	v_mfma_f32_16x16x32_bf16 v[12:15], v[128:131], v[192:195], v[12:15]
	v_mfma_f32_16x16x32_bf16 v[4:7], v[136:139], v[192:195], v[4:7]
	s_waitcnt lgkmcnt(3)
	v_mfma_f32_16x16x32_bf16 v[60:63], v[132:135], v[148:151], v[60:63]
	v_mfma_f32_16x16x32_bf16 v[52:55], v[140:143], v[148:151], v[52:55]
	s_waitcnt lgkmcnt(2)
	v_mfma_f32_16x16x32_bf16 v[44:47], v[132:135], v[166:169], v[44:47]
	v_mfma_f32_16x16x32_bf16 v[36:39], v[140:143], v[166:169], v[36:39]
	s_waitcnt lgkmcnt(1)
	v_mfma_f32_16x16x32_bf16 v[28:31], v[132:135], v[188:191], v[28:31]
	v_mfma_f32_16x16x32_bf16 v[20:23], v[140:143], v[188:191], v[20:23]
	s_waitcnt lgkmcnt(0)
	v_mfma_f32_16x16x32_bf16 v[12:15], v[132:135], v[202:205], v[12:15]
	v_mfma_f32_16x16x32_bf16 v[4:7], v[140:143], v[202:205], v[4:7]
	s_barrier
	s_add_u32 s50, s50, 0x40080
	s_addc_u32 s51, s51, 0
	s_add_i32 s28, s29, s55
	s_mov_b32 m0, s28
	s_nop 0
	global_load_lds_dwordx4 v176, s[50:51]
	s_add_i32 m0, s28, 0x2000
	s_nop 0
	global_load_lds_dwordx4 v160, s[50:51]
	s_waitcnt vmcnt(6)
	s_barrier
	v_mfma_f32_16x16x32_bf16 v[56:59], v[206:209], v[144:147], v[56:59]
	v_mfma_f32_16x16x32_bf16 v[48:51], v[214:217], v[144:147], v[48:51]
	v_mfma_f32_16x16x32_bf16 v[40:43], v[206:209], v[152:155], v[40:43]
	v_mfma_f32_16x16x32_bf16 v[32:35], v[214:217], v[152:155], v[32:35]
	v_mfma_f32_16x16x32_bf16 v[24:27], v[206:209], v[170:173], v[24:27]
	v_mfma_f32_16x16x32_bf16 v[16:19], v[214:217], v[170:173], v[16:19]
	v_mfma_f32_16x16x32_bf16 v[8:11], v[206:209], v[192:195], v[8:11]
	v_mfma_f32_16x16x32_bf16 v[0:3], v[214:217], v[192:195], v[0:3]
	v_mfma_f32_16x16x32_bf16 v[56:59], v[210:213], v[148:151], v[56:59]
	v_mfma_f32_16x16x32_bf16 v[48:51], v[232:235], v[148:151], v[48:51]
	v_mfma_f32_16x16x32_bf16 v[40:43], v[210:213], v[166:169], v[40:43]
	v_mfma_f32_16x16x32_bf16 v[32:35], v[232:235], v[166:169], v[32:35]
	v_mfma_f32_16x16x32_bf16 v[24:27], v[210:213], v[188:191], v[24:27]
	v_mfma_f32_16x16x32_bf16 v[16:19], v[232:235], v[188:191], v[16:19]
	v_mfma_f32_16x16x32_bf16 v[8:11], v[210:213], v[202:205], v[8:11]
	v_mfma_f32_16x16x32_bf16 v[0:3], v[232:235], v[202:205], v[0:3]
	s_add_i32 s70, s70, 2
	s_add_u32 s6, s6, 0x100
	s_addc_u32 s7, s7, 0
	s_add_u32 s68, s68, 0x100
	s_addc_u32 s69, s69, 0
	s_cmp_lt_u32 s70, 14
	s_barrier
	s_cbranch_scc1 .LBB0_1436
	v_mov_b32_e32 v134, v199
	v_mov_b32_e32 v128, v198
	s_lshl_b32 s4, s4, 8
	s_add_i32 s4, s4, s60
	v_add_u32_e32 v192, s4, v128
	v_lshlrev_b32_e32 v128, 2, v134
	v_ashrrev_i32_e32 v129, 31, v128
	v_ashrrev_i32_e32 v193, 31, v192
	v_add_u32_e32 v190, 16, v192
	v_lshl_add_u64 v[132:133], v[128:129], 2, s[8:9]
	v_lshlrev_b64 v[128:129], 6, v[192:193]
	v_ashrrev_i32_e32 v191, 31, v190
	v_add_u32_e32 v188, 32, v192
	v_lshl_add_u64 v[128:129], v[132:133], 0, v[128:129]
	v_lshlrev_b64 v[130:131], 6, v[190:191]
	v_ashrrev_i32_e32 v189, 31, v188
	v_lshl_add_u64 v[130:131], v[132:133], 0, v[130:131]
	global_load_dwordx4 v[202:205], v[128:129], off
	global_load_dwordx4 v[144:147], v[130:131], off
	v_lshlrev_b64 v[128:129], 6, v[188:189]
	v_add_u32_e32 v174, 48, v192
	v_lshl_add_u64 v[128:129], v[132:133], 0, v[128:129]
	v_ashrrev_i32_e32 v175, 31, v174
	global_load_dwordx4 v[148:151], v[128:129], off
	v_lshlrev_b64 v[128:129], 6, v[174:175]
	v_lshl_add_u64 v[128:129], v[132:133], 0, v[128:129]
	global_load_dwordx4 v[152:155], v[128:129], off
	v_add_u32_e32 v172, 0x80, v192
	v_ashrrev_i32_e32 v173, 31, v172
	v_lshlrev_b64 v[128:129], 6, v[172:173]
	v_lshl_add_u64 v[128:129], v[132:133], 0, v[128:129]
	global_load_dwordx4 v[140:143], v[128:129], off
	v_add_u32_e32 v170, 0x90, v192
	v_ashrrev_i32_e32 v171, 31, v170
	v_lshlrev_b64 v[128:129], 6, v[170:171]
	v_lshl_add_u64 v[128:129], v[132:133], 0, v[128:129]
	global_load_dwordx4 v[128:131], v[128:129], off
	s_lshl_b32 s5, s5, 7
	v_add_u32_e32 v168, 0xa0, v192
	v_add_u32_e32 v166, 0xb0, v192
	s_or_b32 s5, s5, s61
	v_ashrrev_i32_e32 v169, 31, v168
	v_ashrrev_i32_e32 v167, 31, v166
	v_lshl_add_u32 v194, v134, 3, s5
	v_lshlrev_b64 v[134:135], 6, v[168:169]
	v_lshlrev_b64 v[136:137], 6, v[166:167]
	v_lshl_add_u64 v[134:135], v[132:133], 0, v[134:135]
	v_lshl_add_u64 v[132:133], v[132:133], 0, v[136:137]
	global_load_dwordx4 v[136:139], v[134:135], off
	s_nop 0
	global_load_dwordx4 v[132:135], v[132:133], off
	s_mov_b32 s4, 0x358637bd
	v_mov_b64_e32 v[196:197], s[4:5]
	v_ashrrev_i32_e32 v195, 31, v194
	s_mov_b64 s[50:51], s[20:21]
	s_waitcnt vmcnt(0)
	v_mov_b32_e32 v206, v203
	v_mov_b32_e32 v207, v204
	v_mov_b32_e32 v203, v205
	v_mov_b32_e32 v204, v145
	v_mov_b32_e32 v205, v146
	v_mov_b32_e32 v145, v147
	v_pk_add_f32 v[202:203], v[206:207], v[202:203]
	v_mov_b32_e32 v146, v149
	v_mov_b32_e32 v147, v150
	v_mov_b32_e32 v149, v151
	v_mov_b32_e32 v150, v153
	v_mov_b32_e32 v151, v154
	v_mov_b32_e32 v153, v155
	v_pk_add_f32 v[144:145], v[204:205], v[144:145]
	v_mov_b32_e32 v155, v202
	v_pk_add_f32 v[146:147], v[146:147], v[148:149]
	v_pk_add_f32 v[148:149], v[150:151], v[152:153]
	v_mov_b32_e32 v154, v144
	v_mov_b32_e32 v202, v145
	v_mov_b32_e32 v144, v148
	v_mov_b32_e32 v145, v146
	v_mov_b32_e32 v146, v149
	v_pk_add_f32 v[148:149], v[154:155], v[202:203]
	v_pk_add_f32 v[144:145], v[144:145], v[146:147]
	v_mov_b32_e32 v147, v149
	v_mov_b32_e32 v146, v148
	v_mov_b32_e32 v151, v145
	v_mov_b32_e32 v150, v144
	v_mov_b32_e32 v152, v141
	v_mov_b32_e32 v153, v142
	v_mov_b32_e32 v141, v143
	s_waitcnt lgkmcnt(0)
	v_permlane16_swap_b32 v149, v147
	v_permlane16_swap_b32 v148, v146
	v_pk_add_f32 v[142:143], v[148:149], v[146:147]
	v_mov_b32_e32 v147, v143
	v_mov_b32_e32 v146, v142
	v_permlane16_swap_b32 v145, v151
	v_permlane16_swap_b32 v144, v150
	v_pk_add_f32 v[144:145], v[144:145], v[150:151]
	v_mov_b32_e32 v149, v145
	v_mov_b32_e32 v148, v144
	v_mov_b32_e32 v150, v129
	s_waitcnt lgkmcnt(0)
	v_permlane32_swap_b32 v143, v147
	v_permlane32_swap_b32 v142, v146
	v_pk_add_f32 v[142:143], v[142:143], v[146:147]
	v_mov_b32_e32 v151, v130
	v_pk_fma_f32 v[142:143], v[142:143], s[30:31], v[196:197] op_sel_hi:[1,0,0]
	s_waitcnt lgkmcnt(0)
	v_permlane32_swap_b32 v145, v149
	v_permlane32_swap_b32 v144, v148
	v_pk_add_f32 v[144:145], v[144:145], v[148:149]
	v_mul_f32_e32 v129, 0x4b800000, v143
	v_cmp_gt_f32_e32 vcc, s86, v143
	v_pk_fma_f32 v[146:147], v[144:145], s[30:31], v[196:197] op_sel_hi:[1,0,0]
	v_mul_f32_e32 v130, 0x4b800000, v142
	v_cndmask_b32_e32 v129, v143, v129, vcc
	v_rsq_f32_e32 v129, v129
	v_cmp_gt_f32_e64 s[4:5], s86, v142
	v_mul_f32_e32 v144, 0x4b800000, v147
	v_cmp_gt_f32_e64 s[6:7], s86, v147
	v_cndmask_b32_e64 v130, v142, v130, s[4:5]
	v_rsq_f32_e32 v142, v130
	v_cndmask_b32_e64 v130, v147, v144, s[6:7]
	v_rsq_f32_e32 v143, v130
	v_mul_f32_e32 v130, 0x45800000, v129
	v_cndmask_b32_e32 v144, v129, v130, vcc
	v_mov_b32_e32 v129, v131
	v_pk_add_f32 v[140:141], v[152:153], v[140:141]
	v_pk_add_f32 v[128:129], v[150:151], v[128:129]
	v_mov_b32_e32 v131, v140
	v_mov_b32_e32 v130, v128
	v_mov_b32_e32 v140, v129
	v_pk_add_f32 v[128:129], v[130:131], v[140:141]
	v_mov_b32_e32 v131, v129
	v_mov_b32_e32 v130, v128
	v_mul_f32_e32 v145, 0x45800000, v142
	v_cndmask_b32_e64 v142, v142, v145, s[4:5]
	v_mul_f32_e32 v140, 0x4b800000, v146
	v_cmp_gt_f32_e32 vcc, s86, v146
	s_waitcnt lgkmcnt(0)
	v_permlane16_swap_b32 v129, v131
	v_permlane16_swap_b32 v128, v130
	v_pk_add_f32 v[128:129], v[128:129], v[130:131]
	v_mov_b32_e32 v131, v129
	v_mov_b32_e32 v130, v128
	v_cndmask_b32_e32 v140, v146, v140, vcc
	v_rsq_f32_e32 v141, v140
	v_mul_f32_e32 v140, 0x45800000, v143
	v_cndmask_b32_e64 v140, v143, v140, s[6:7]
	s_waitcnt lgkmcnt(0)
	v_permlane32_swap_b32 v129, v131
	v_permlane32_swap_b32 v128, v130
	v_pk_add_f32 v[128:129], v[128:129], v[130:131]
	v_mov_b32_e32 v131, v138
	v_pk_fma_f32 v[128:129], v[128:129], s[30:31], v[196:197] op_sel_hi:[1,0,0]
	v_mul_f32_e32 v143, 0x45800000, v141
	v_mul_f32_e32 v130, 0x4b800000, v129
	v_cmp_gt_f32_e64 s[4:5], s86, v129
	v_cmp_gt_f32_e64 s[6:7], s86, v128
	v_pk_mul_f32 v[110:111], v[110:111], v[142:143] op_sel_hi:[1,0]
	v_cndmask_b32_e64 v129, v129, v130, s[4:5]
	v_mov_b32_e32 v130, v137
	v_mov_b32_e32 v137, v139
	v_pk_add_f32 v[130:131], v[130:131], v[136:137]
	v_mov_b32_e32 v136, v133
	v_mov_b32_e32 v137, v134
	v_mov_b32_e32 v133, v135
	v_pk_add_f32 v[132:133], v[136:137], v[132:133]
	v_mov_b32_e32 v135, v130
	v_mov_b32_e32 v134, v132
	v_mov_b32_e32 v130, v133
	v_pk_add_f32 v[130:131], v[134:135], v[130:131]
	v_mov_b32_e32 v133, v131
	v_mov_b32_e32 v132, v130
	v_rsq_f32_e32 v145, v129
	v_mul_f32_e32 v129, 0x4b800000, v128
	v_cndmask_b32_e64 v128, v128, v129, s[6:7]
	v_rsq_f32_e32 v135, v128
	s_waitcnt lgkmcnt(0)
	v_permlane16_swap_b32 v131, v133
	v_permlane16_swap_b32 v130, v132
	v_pk_add_f32 v[128:129], v[130:131], v[132:133]
	v_mov_b32_e32 v131, v129
	v_mov_b32_e32 v130, v128
	v_pk_mul_f32 v[126:127], v[126:127], v[144:145] op_sel_hi:[1,0]
	v_pk_mul_f32 v[122:123], v[122:123], v[144:145] op_sel_hi:[1,0]
	v_pk_mul_f32 v[116:117], v[116:117], v[144:145] op_sel_hi:[1,0]
	v_pk_mul_f32 v[124:125], v[124:125], v[144:145] op_sel_hi:[1,0]
	v_pk_mul_f32 v[138:139], v[126:127], s[44:45] op_sel_hi:[1,0]
	v_pk_mul_f32 v[120:121], v[120:121], v[144:145] op_sel_hi:[1,0]
	v_pk_mul_f32 v[122:123], v[126:127], v[122:123]
	v_pk_mul_f32 v[118:119], v[118:119], v[144:145] op_sel_hi:[1,0]
	v_pk_mul_f32 v[126:127], v[116:117], s[44:45] op_sel_hi:[1,0]
	v_pk_mul_f32 v[146:147], v[124:125], s[44:45] op_sel_hi:[1,0]
	v_pk_mul_f32 v[120:121], v[124:125], v[120:121]
	v_pk_mul_f32 v[124:125], v[118:119], s[44:45] op_sel_hi:[1,0]
	v_exp_f32_e32 v126, v126
	v_exp_f32_e32 v127, v127
	s_waitcnt lgkmcnt(0)
	v_permlane32_swap_b32 v129, v131
	v_permlane32_swap_b32 v128, v130
	v_pk_add_f32 v[128:129], v[128:129], v[130:131]
	v_exp_f32_e32 v146, v146
	v_exp_f32_e32 v138, v138
	v_exp_f32_e32 v139, v139
	v_exp_f32_e32 v147, v147
	v_exp_f32_e32 v124, v124
	v_exp_f32_e32 v125, v125
	v_pk_fma_f32 v[128:129], v[128:129], s[30:31], v[196:197] op_sel_hi:[1,0,0]
	v_cndmask_b32_e32 v136, v141, v143, vcc
	v_mul_f32_e32 v132, 0x45800000, v145
	v_mul_f32_e32 v130, 0x4b800000, v129
	v_cmp_gt_f32_e32 vcc, s86, v129
	v_cndmask_b32_e64 v134, v145, v132, s[4:5]
	v_cmp_gt_f32_e64 s[4:5], s86, v128
	v_cndmask_b32_e32 v129, v129, v130, vcc
	v_mul_f32_e32 v130, 0x4b800000, v128
	v_pk_add_f32 v[126:127], v[126:127], 1.0 op_sel_hi:[1,0]
	v_rsq_f32_e32 v129, v129
	v_cndmask_b32_e64 v128, v128, v130, s[4:5]
	v_pk_add_f32 v[138:139], v[138:139], 1.0 op_sel_hi:[1,0]
	v_pk_add_f32 v[146:147], v[146:147], 1.0 op_sel_hi:[1,0]
	v_pk_add_f32 v[124:125], v[124:125], 1.0 op_sel_hi:[1,0]
	v_rcp_f32_e32 v126, v126
	v_rcp_f32_e32 v127, v127
	v_rsq_f32_e32 v128, v128
	v_rcp_f32_e32 v146, v146
	v_rcp_f32_e32 v138, v138
	v_rcp_f32_e32 v139, v139
	v_rcp_f32_e32 v147, v147
	v_rcp_f32_e32 v124, v124
	v_rcp_f32_e32 v125, v125
	v_pk_mul_f32 v[112:113], v[112:113], v[144:145] op_sel_hi:[1,0]
	v_pk_mul_f32 v[114:115], v[114:115], v[144:145] op_sel_hi:[1,0]
	v_pk_mul_f32 v[112:113], v[116:117], v[112:113]
	v_mul_f32_e32 v130, 0x45800000, v129
	v_pk_mul_f32 v[114:115], v[118:119], v[114:115]
	v_pk_mul_f32 v[112:113], v[112:113], v[126:127]
	v_cndmask_b32_e32 v130, v129, v130, vcc
	v_mul_f32_e32 v129, 0x45800000, v128
	v_pk_mul_f32 v[122:123], v[122:123], v[138:139]
	v_pk_mul_f32 v[120:121], v[120:121], v[146:147]
	v_pk_mul_f32 v[114:115], v[114:115], v[124:125]
	v_cvt_pk_bf16_f32 v116, v120, v121
	v_cvt_pk_bf16_f32 v117, v122, v123
	v_cvt_pk_bf16_f32 v118, v112, v113
	v_mov_b64_e32 v[112:113], s[10:11]
	v_cndmask_b32_e64 v128, v128, v129, s[4:5]
	v_cvt_pk_bf16_f32 v119, v114, v115
	v_mad_i64_i32 v[120:121], s[4:5], v192, s35, v[112:113]
	v_lshlrev_b64 v[114:115], 1, v[194:195]
	v_lshl_add_u64 v[120:121], v[120:121], 0, v[114:115]
	v_pk_mul_f32 v[108:109], v[108:109], v[142:143] op_sel_hi:[1,0]
	v_pk_mul_f32 v[106:107], v[106:107], v[142:143] op_sel_hi:[1,0]
	v_pk_mul_f32 v[104:105], v[104:105], v[142:143] op_sel_hi:[1,0]
	v_pk_mul_f32 v[102:103], v[102:103], v[142:143] op_sel_hi:[1,0]
	v_pk_mul_f32 v[100:101], v[100:101], v[142:143] op_sel_hi:[1,0]
	global_store_dwordx4 v[120:121], v[116:119], off
	v_pk_mul_f32 v[104:105], v[108:109], v[104:105]
	v_pk_mul_f32 v[106:107], v[110:111], v[106:107]
	v_pk_mul_f32 v[116:117], v[110:111], s[44:45] op_sel_hi:[1,0]
	v_pk_mul_f32 v[118:119], v[108:109], s[44:45] op_sel_hi:[1,0]
	v_pk_mul_f32 v[108:109], v[102:103], s[44:45] op_sel_hi:[1,0]
	v_pk_mul_f32 v[110:111], v[100:101], s[44:45] op_sel_hi:[1,0]
	v_exp_f32_e32 v108, v108
	v_exp_f32_e32 v110, v110
	v_exp_f32_e32 v109, v109
	v_exp_f32_e32 v111, v111
	v_exp_f32_e32 v118, v118
	v_exp_f32_e32 v116, v116
	v_exp_f32_e32 v117, v117
	v_exp_f32_e32 v119, v119
	v_pk_add_f32 v[108:109], v[108:109], 1.0 op_sel_hi:[1,0]
	v_pk_add_f32 v[110:111], v[110:111], 1.0 op_sel_hi:[1,0]
	v_pk_add_f32 v[116:117], v[116:117], 1.0 op_sel_hi:[1,0]
	v_pk_add_f32 v[118:119], v[118:119], 1.0 op_sel_hi:[1,0]
	v_rcp_f32_e32 v110, v110
	v_rcp_f32_e32 v108, v108
	v_rcp_f32_e32 v109, v109
	v_rcp_f32_e32 v111, v111
	v_rcp_f32_e32 v118, v118
	v_rcp_f32_e32 v116, v116
	v_rcp_f32_e32 v117, v117
	v_rcp_f32_e32 v119, v119
	v_pk_mul_f32 v[98:99], v[98:99], v[142:143] op_sel_hi:[1,0]
	v_pk_mul_f32 v[96:97], v[96:97], v[142:143] op_sel_hi:[1,0]
	v_pk_mul_f32 v[98:99], v[102:103], v[98:99]
	v_pk_mul_f32 v[96:97], v[100:101], v[96:97]
	v_pk_mul_f32 v[100:101], v[98:99], v[108:109]
	v_pk_mul_f32 v[98:99], v[96:97], v[110:111]
	v_pk_mul_f32 v[106:107], v[106:107], v[116:117]
	v_pk_mul_f32 v[104:105], v[104:105], v[118:119]
	v_pk_mul_f32 v[94:95], v[94:95], v[140:141] op_sel_hi:[1,0]
	v_cvt_pk_bf16_f32 v96, v104, v105
	v_cvt_pk_bf16_f32 v97, v106, v107
	v_cvt_pk_bf16_f32 v98, v98, v99
	v_cvt_pk_bf16_f32 v99, v100, v101
	v_mad_i64_i32 v[100:101], s[4:5], v190, s35, v[112:113]
	v_lshl_add_u64 v[100:101], v[100:101], 0, v[114:115]
	v_pk_mul_f32 v[92:93], v[92:93], v[140:141] op_sel_hi:[1,0]
	v_pk_mul_f32 v[90:91], v[90:91], v[140:141] op_sel_hi:[1,0]
	v_pk_mul_f32 v[88:89], v[88:89], v[140:141] op_sel_hi:[1,0]
	v_pk_mul_f32 v[86:87], v[86:87], v[140:141] op_sel_hi:[1,0]
	v_pk_mul_f32 v[84:85], v[84:85], v[140:141] op_sel_hi:[1,0]
	global_store_dwordx4 v[100:101], v[96:99], off
	v_pk_mul_f32 v[88:89], v[92:93], v[88:89]
	v_pk_mul_f32 v[90:91], v[94:95], v[90:91]
	v_pk_mul_f32 v[96:97], v[94:95], s[44:45] op_sel_hi:[1,0]
	v_pk_mul_f32 v[98:99], v[92:93], s[44:45] op_sel_hi:[1,0]
	v_pk_mul_f32 v[92:93], v[86:87], s[44:45] op_sel_hi:[1,0]
	v_pk_mul_f32 v[94:95], v[84:85], s[44:45] op_sel_hi:[1,0]
	v_exp_f32_e32 v92, v92
	v_exp_f32_e32 v94, v94
	v_exp_f32_e32 v93, v93
	v_exp_f32_e32 v95, v95
	v_exp_f32_e32 v98, v98
	v_exp_f32_e32 v96, v96
	v_exp_f32_e32 v97, v97
	v_exp_f32_e32 v99, v99
	v_pk_add_f32 v[92:93], v[92:93], 1.0 op_sel_hi:[1,0]
	v_pk_add_f32 v[94:95], v[94:95], 1.0 op_sel_hi:[1,0]
	v_pk_add_f32 v[96:97], v[96:97], 1.0 op_sel_hi:[1,0]
	v_pk_add_f32 v[98:99], v[98:99], 1.0 op_sel_hi:[1,0]
	v_rcp_f32_e32 v94, v94
	v_rcp_f32_e32 v92, v92
	v_rcp_f32_e32 v93, v93
	v_rcp_f32_e32 v95, v95
	v_rcp_f32_e32 v98, v98
	v_rcp_f32_e32 v96, v96
	v_rcp_f32_e32 v97, v97
	v_rcp_f32_e32 v99, v99
	v_pk_mul_f32 v[82:83], v[82:83], v[140:141] op_sel_hi:[1,0]
	v_pk_mul_f32 v[80:81], v[80:81], v[140:141] op_sel_hi:[1,0]
	v_pk_mul_f32 v[82:83], v[86:87], v[82:83]
	v_pk_mul_f32 v[80:81], v[84:85], v[80:81]
	v_pk_mul_f32 v[84:85], v[82:83], v[92:93]
	v_pk_mul_f32 v[82:83], v[80:81], v[94:95]
	v_pk_mul_f32 v[90:91], v[90:91], v[96:97]
	v_pk_mul_f32 v[88:89], v[88:89], v[98:99]
	v_pk_mul_f32 v[78:79], v[78:79], v[136:137] op_sel_hi:[1,0]
	v_cvt_pk_bf16_f32 v80, v88, v89
	v_cvt_pk_bf16_f32 v81, v90, v91
	v_cvt_pk_bf16_f32 v82, v82, v83
	v_cvt_pk_bf16_f32 v83, v84, v85
	v_mad_i64_i32 v[84:85], s[4:5], v188, s35, v[112:113]
	v_lshl_add_u64 v[84:85], v[84:85], 0, v[114:115]
	v_pk_mul_f32 v[76:77], v[76:77], v[136:137] op_sel_hi:[1,0]
	v_pk_mul_f32 v[74:75], v[74:75], v[136:137] op_sel_hi:[1,0]
	v_pk_mul_f32 v[72:73], v[72:73], v[136:137] op_sel_hi:[1,0]
	v_pk_mul_f32 v[70:71], v[70:71], v[136:137] op_sel_hi:[1,0]
	v_pk_mul_f32 v[68:69], v[68:69], v[136:137] op_sel_hi:[1,0]
	global_store_dwordx4 v[84:85], v[80:83], off
	v_pk_mul_f32 v[72:73], v[76:77], v[72:73]
	v_pk_mul_f32 v[74:75], v[78:79], v[74:75]
	v_pk_mul_f32 v[80:81], v[78:79], s[44:45] op_sel_hi:[1,0]
	v_pk_mul_f32 v[82:83], v[76:77], s[44:45] op_sel_hi:[1,0]
	v_pk_mul_f32 v[76:77], v[70:71], s[44:45] op_sel_hi:[1,0]
	v_pk_mul_f32 v[78:79], v[68:69], s[44:45] op_sel_hi:[1,0]
	v_exp_f32_e32 v76, v76
	v_exp_f32_e32 v78, v78
	v_exp_f32_e32 v77, v77
	v_exp_f32_e32 v79, v79
	v_exp_f32_e32 v82, v82
	v_exp_f32_e32 v80, v80
	v_exp_f32_e32 v81, v81
	v_exp_f32_e32 v83, v83
	v_pk_add_f32 v[76:77], v[76:77], 1.0 op_sel_hi:[1,0]
	v_pk_add_f32 v[78:79], v[78:79], 1.0 op_sel_hi:[1,0]
	v_pk_add_f32 v[80:81], v[80:81], 1.0 op_sel_hi:[1,0]
	v_pk_add_f32 v[82:83], v[82:83], 1.0 op_sel_hi:[1,0]
	v_rcp_f32_e32 v78, v78
	v_rcp_f32_e32 v76, v76
	v_rcp_f32_e32 v77, v77
	v_rcp_f32_e32 v79, v79
	v_rcp_f32_e32 v82, v82
	v_rcp_f32_e32 v80, v80
	v_rcp_f32_e32 v81, v81
	v_rcp_f32_e32 v83, v83
	v_pk_mul_f32 v[66:67], v[66:67], v[136:137] op_sel_hi:[1,0]
	v_pk_mul_f32 v[64:65], v[64:65], v[136:137] op_sel_hi:[1,0]
	v_pk_mul_f32 v[66:67], v[70:71], v[66:67]
	v_pk_mul_f32 v[64:65], v[68:69], v[64:65]
	v_pk_mul_f32 v[68:69], v[66:67], v[76:77]
	v_pk_mul_f32 v[66:67], v[64:65], v[78:79]
	v_pk_mul_f32 v[74:75], v[74:75], v[80:81]
	v_pk_mul_f32 v[72:73], v[72:73], v[82:83]
	v_pk_mul_f32 v[62:63], v[62:63], v[134:135] op_sel_hi:[1,0]
	v_cvt_pk_bf16_f32 v64, v72, v73
	v_cvt_pk_bf16_f32 v65, v74, v75
	v_cvt_pk_bf16_f32 v66, v66, v67
	v_cvt_pk_bf16_f32 v67, v68, v69
	v_mad_i64_i32 v[68:69], s[4:5], v174, s35, v[112:113]
	v_lshl_add_u64 v[68:69], v[68:69], 0, v[114:115]
	v_pk_mul_f32 v[60:61], v[60:61], v[134:135] op_sel_hi:[1,0]
	v_pk_mul_f32 v[58:59], v[58:59], v[134:135] op_sel_hi:[1,0]
	v_pk_mul_f32 v[56:57], v[56:57], v[134:135] op_sel_hi:[1,0]
	v_pk_mul_f32 v[54:55], v[54:55], v[134:135] op_sel_hi:[1,0]
	v_pk_mul_f32 v[52:53], v[52:53], v[134:135] op_sel_hi:[1,0]
	global_store_dwordx4 v[68:69], v[64:67], off
	v_pk_mul_f32 v[56:57], v[60:61], v[56:57]
	v_pk_mul_f32 v[58:59], v[62:63], v[58:59]
	v_pk_mul_f32 v[64:65], v[62:63], s[44:45] op_sel_hi:[1,0]
	v_pk_mul_f32 v[66:67], v[60:61], s[44:45] op_sel_hi:[1,0]
	v_pk_mul_f32 v[60:61], v[54:55], s[44:45] op_sel_hi:[1,0]
	v_pk_mul_f32 v[62:63], v[52:53], s[44:45] op_sel_hi:[1,0]
	v_exp_f32_e32 v60, v60
	v_exp_f32_e32 v62, v62
	v_exp_f32_e32 v61, v61
	v_exp_f32_e32 v63, v63
	v_exp_f32_e32 v66, v66
	v_exp_f32_e32 v64, v64
	v_exp_f32_e32 v65, v65
	v_exp_f32_e32 v67, v67
	v_pk_add_f32 v[60:61], v[60:61], 1.0 op_sel_hi:[1,0]
	v_pk_add_f32 v[62:63], v[62:63], 1.0 op_sel_hi:[1,0]
	v_pk_add_f32 v[64:65], v[64:65], 1.0 op_sel_hi:[1,0]
	v_pk_add_f32 v[66:67], v[66:67], 1.0 op_sel_hi:[1,0]
	v_rcp_f32_e32 v62, v62
	v_rcp_f32_e32 v60, v60
	v_rcp_f32_e32 v61, v61
	v_rcp_f32_e32 v63, v63
	v_rcp_f32_e32 v66, v66
	v_rcp_f32_e32 v64, v64
	v_rcp_f32_e32 v65, v65
	v_rcp_f32_e32 v67, v67
	v_pk_mul_f32 v[50:51], v[50:51], v[134:135] op_sel_hi:[1,0]
	v_pk_mul_f32 v[48:49], v[48:49], v[134:135] op_sel_hi:[1,0]
	v_pk_mul_f32 v[50:51], v[54:55], v[50:51]
	v_pk_mul_f32 v[48:49], v[52:53], v[48:49]
	v_mul_f32_e32 v132, 0x45800000, v135
	v_pk_mul_f32 v[52:53], v[50:51], v[60:61]
	v_pk_mul_f32 v[50:51], v[48:49], v[62:63]
	v_cndmask_b32_e64 v132, v135, v132, s[6:7]
	v_pk_mul_f32 v[58:59], v[58:59], v[64:65]
	v_pk_mul_f32 v[56:57], v[56:57], v[66:67]
	v_pk_mul_f32 v[46:47], v[46:47], v[132:133] op_sel_hi:[1,0]
	v_cvt_pk_bf16_f32 v48, v56, v57
	v_cvt_pk_bf16_f32 v49, v58, v59
	v_cvt_pk_bf16_f32 v50, v50, v51
	v_cvt_pk_bf16_f32 v51, v52, v53
	v_mad_i64_i32 v[52:53], s[4:5], v172, s35, v[112:113]
	v_lshl_add_u64 v[52:53], v[52:53], 0, v[114:115]
	v_pk_mul_f32 v[44:45], v[44:45], v[132:133] op_sel_hi:[1,0]
	v_pk_mul_f32 v[42:43], v[42:43], v[132:133] op_sel_hi:[1,0]
	v_pk_mul_f32 v[40:41], v[40:41], v[132:133] op_sel_hi:[1,0]
	v_pk_mul_f32 v[38:39], v[38:39], v[132:133] op_sel_hi:[1,0]
	v_pk_mul_f32 v[36:37], v[36:37], v[132:133] op_sel_hi:[1,0]
	global_store_dwordx4 v[52:53], v[48:51], off
	v_pk_mul_f32 v[40:41], v[44:45], v[40:41]
	v_pk_mul_f32 v[42:43], v[46:47], v[42:43]
	v_pk_mul_f32 v[48:49], v[46:47], s[44:45] op_sel_hi:[1,0]
	v_pk_mul_f32 v[50:51], v[44:45], s[44:45] op_sel_hi:[1,0]
	v_pk_mul_f32 v[44:45], v[38:39], s[44:45] op_sel_hi:[1,0]
	v_pk_mul_f32 v[46:47], v[36:37], s[44:45] op_sel_hi:[1,0]
	v_exp_f32_e32 v44, v44
	v_exp_f32_e32 v46, v46
	v_exp_f32_e32 v45, v45
	v_exp_f32_e32 v47, v47
	v_exp_f32_e32 v50, v50
	v_exp_f32_e32 v48, v48
	v_exp_f32_e32 v49, v49
	v_exp_f32_e32 v51, v51
	v_pk_add_f32 v[44:45], v[44:45], 1.0 op_sel_hi:[1,0]
	v_pk_add_f32 v[46:47], v[46:47], 1.0 op_sel_hi:[1,0]
	v_pk_add_f32 v[48:49], v[48:49], 1.0 op_sel_hi:[1,0]
	v_pk_add_f32 v[50:51], v[50:51], 1.0 op_sel_hi:[1,0]
	v_rcp_f32_e32 v46, v46
	v_rcp_f32_e32 v44, v44
	v_rcp_f32_e32 v45, v45
	v_rcp_f32_e32 v47, v47
	v_rcp_f32_e32 v50, v50
	v_rcp_f32_e32 v48, v48
	v_rcp_f32_e32 v49, v49
	v_rcp_f32_e32 v51, v51
	v_pk_mul_f32 v[34:35], v[34:35], v[132:133] op_sel_hi:[1,0]
	v_pk_mul_f32 v[32:33], v[32:33], v[132:133] op_sel_hi:[1,0]
	v_pk_mul_f32 v[34:35], v[38:39], v[34:35]
	v_pk_mul_f32 v[32:33], v[36:37], v[32:33]
	v_pk_mul_f32 v[36:37], v[34:35], v[44:45]
	v_pk_mul_f32 v[34:35], v[32:33], v[46:47]
	v_pk_mul_f32 v[42:43], v[42:43], v[48:49]
	v_pk_mul_f32 v[40:41], v[40:41], v[50:51]
	v_pk_mul_f32 v[30:31], v[30:31], v[130:131] op_sel_hi:[1,0]
	v_cvt_pk_bf16_f32 v32, v40, v41
	v_cvt_pk_bf16_f32 v33, v42, v43
	v_cvt_pk_bf16_f32 v34, v34, v35
	v_cvt_pk_bf16_f32 v35, v36, v37
	v_mad_i64_i32 v[36:37], s[4:5], v170, s35, v[112:113]
	v_lshl_add_u64 v[36:37], v[36:37], 0, v[114:115]
	v_pk_mul_f32 v[28:29], v[28:29], v[130:131] op_sel_hi:[1,0]
	v_pk_mul_f32 v[26:27], v[26:27], v[130:131] op_sel_hi:[1,0]
	v_pk_mul_f32 v[24:25], v[24:25], v[130:131] op_sel_hi:[1,0]
	v_pk_mul_f32 v[22:23], v[22:23], v[130:131] op_sel_hi:[1,0]
	v_pk_mul_f32 v[20:21], v[20:21], v[130:131] op_sel_hi:[1,0]
	global_store_dwordx4 v[36:37], v[32:35], off
	v_pk_mul_f32 v[24:25], v[28:29], v[24:25]
	v_pk_mul_f32 v[26:27], v[30:31], v[26:27]
	v_pk_mul_f32 v[32:33], v[30:31], s[44:45] op_sel_hi:[1,0]
	v_pk_mul_f32 v[34:35], v[28:29], s[44:45] op_sel_hi:[1,0]
	v_pk_mul_f32 v[28:29], v[22:23], s[44:45] op_sel_hi:[1,0]
	v_pk_mul_f32 v[30:31], v[20:21], s[44:45] op_sel_hi:[1,0]
	v_exp_f32_e32 v28, v28
	v_exp_f32_e32 v30, v30
	v_exp_f32_e32 v29, v29
	v_exp_f32_e32 v31, v31
	v_exp_f32_e32 v34, v34
	v_exp_f32_e32 v32, v32
	v_exp_f32_e32 v33, v33
	v_exp_f32_e32 v35, v35
	v_pk_add_f32 v[28:29], v[28:29], 1.0 op_sel_hi:[1,0]
	v_pk_add_f32 v[30:31], v[30:31], 1.0 op_sel_hi:[1,0]
	v_pk_add_f32 v[32:33], v[32:33], 1.0 op_sel_hi:[1,0]
	v_pk_add_f32 v[34:35], v[34:35], 1.0 op_sel_hi:[1,0]
	v_rcp_f32_e32 v30, v30
	v_rcp_f32_e32 v28, v28
	v_rcp_f32_e32 v29, v29
	v_rcp_f32_e32 v31, v31
	v_rcp_f32_e32 v34, v34
	v_rcp_f32_e32 v32, v32
	v_rcp_f32_e32 v33, v33
	v_rcp_f32_e32 v35, v35
	v_pk_mul_f32 v[18:19], v[18:19], v[130:131] op_sel_hi:[1,0]
	v_pk_mul_f32 v[16:17], v[16:17], v[130:131] op_sel_hi:[1,0]
	v_pk_mul_f32 v[18:19], v[22:23], v[18:19]
	v_pk_mul_f32 v[16:17], v[20:21], v[16:17]
	v_pk_mul_f32 v[20:21], v[18:19], v[28:29]
	v_pk_mul_f32 v[18:19], v[16:17], v[30:31]
	v_pk_mul_f32 v[26:27], v[26:27], v[32:33]
	v_pk_mul_f32 v[24:25], v[24:25], v[34:35]
	v_pk_mul_f32 v[14:15], v[14:15], v[128:129] op_sel_hi:[1,0]
	v_cvt_pk_bf16_f32 v16, v24, v25
	v_cvt_pk_bf16_f32 v17, v26, v27
	v_cvt_pk_bf16_f32 v18, v18, v19
	v_cvt_pk_bf16_f32 v19, v20, v21
	v_mad_i64_i32 v[20:21], s[4:5], v168, s35, v[112:113]
	v_lshl_add_u64 v[20:21], v[20:21], 0, v[114:115]
	v_pk_mul_f32 v[12:13], v[12:13], v[128:129] op_sel_hi:[1,0]
	v_pk_mul_f32 v[10:11], v[10:11], v[128:129] op_sel_hi:[1,0]
	v_pk_mul_f32 v[8:9], v[8:9], v[128:129] op_sel_hi:[1,0]
	v_pk_mul_f32 v[6:7], v[6:7], v[128:129] op_sel_hi:[1,0]
	v_pk_mul_f32 v[4:5], v[4:5], v[128:129] op_sel_hi:[1,0]
	global_store_dwordx4 v[20:21], v[16:19], off
	v_pk_mul_f32 v[8:9], v[12:13], v[8:9]
	v_pk_mul_f32 v[10:11], v[14:15], v[10:11]
	v_pk_mul_f32 v[16:17], v[14:15], s[44:45] op_sel_hi:[1,0]
	v_pk_mul_f32 v[18:19], v[12:13], s[44:45] op_sel_hi:[1,0]
	v_pk_mul_f32 v[12:13], v[6:7], s[44:45] op_sel_hi:[1,0]
	v_pk_mul_f32 v[14:15], v[4:5], s[44:45] op_sel_hi:[1,0]
	v_exp_f32_e32 v12, v12
	v_exp_f32_e32 v14, v14
	v_exp_f32_e32 v13, v13
	v_exp_f32_e32 v15, v15
	v_exp_f32_e32 v18, v18
	v_exp_f32_e32 v16, v16
	v_exp_f32_e32 v17, v17
	v_exp_f32_e32 v19, v19
	v_pk_add_f32 v[12:13], v[12:13], 1.0 op_sel_hi:[1,0]
	v_pk_add_f32 v[14:15], v[14:15], 1.0 op_sel_hi:[1,0]
	v_pk_add_f32 v[16:17], v[16:17], 1.0 op_sel_hi:[1,0]
	v_pk_add_f32 v[18:19], v[18:19], 1.0 op_sel_hi:[1,0]
	v_rcp_f32_e32 v14, v14
	v_rcp_f32_e32 v12, v12
	v_rcp_f32_e32 v13, v13
	v_rcp_f32_e32 v15, v15
	v_rcp_f32_e32 v18, v18
	v_rcp_f32_e32 v16, v16
	v_rcp_f32_e32 v17, v17
	v_rcp_f32_e32 v19, v19
	v_pk_mul_f32 v[2:3], v[2:3], v[128:129] op_sel_hi:[1,0]
	v_pk_mul_f32 v[0:1], v[0:1], v[128:129] op_sel_hi:[1,0]
	v_pk_mul_f32 v[2:3], v[6:7], v[2:3]
	v_pk_mul_f32 v[0:1], v[4:5], v[0:1]
	v_pk_mul_f32 v[4:5], v[2:3], v[12:13]
	v_pk_mul_f32 v[2:3], v[0:1], v[14:15]
	v_pk_mul_f32 v[10:11], v[10:11], v[16:17]
	v_pk_mul_f32 v[8:9], v[8:9], v[18:19]
	s_andn2_b64 vcc, exec, s[2:3]
	v_cvt_pk_bf16_f32 v0, v8, v9
	v_cvt_pk_bf16_f32 v1, v10, v11
	v_cvt_pk_bf16_f32 v2, v2, v3
	v_cvt_pk_bf16_f32 v3, v4, v5
	v_mad_i64_i32 v[4:5], s[4:5], v166, s35, v[112:113]
	v_lshl_add_u64 v[4:5], v[4:5], 0, v[114:115]
	s_mov_b32 s4, s16
	s_mov_b32 s5, s12
	s_mov_b64 s[6:7], s[18:19]
	global_store_dwordx4 v[4:5], v[0:3], off
	s_cbranch_vccnz .LBB0_1429
	s_waitcnt vmcnt(0)
	s_cmpk_gt_u32 s24, 0xff
	s_cbranch_scc1 .LBB0_1440
	s_barrier
